# all-to-all release barriers plus two polling loads in flight (half-period polling of the release counter)
# speedup vs baseline: 1.0286x; 1.0007x over previous
; __device__ __forceinline__ unsigned xb_ld(unsigned* p)              { return __hip_atomic_load(p, __ATOMIC_RELAXED, __HIP_MEMORY_SCOPE_AGENT); }
; __device__ __forceinline__ unsigned xb_add(unsigned* p, unsigned v) { return __hip_atomic_fetch_add(p, v, __ATOMIC_RELAXED, __HIP_MEMORY_SCOPE_AGENT); }
; #define XB_SPIN(cond, bar) do { unsigned _sp = 0; while (cond) { __builtin_amdgcn_s_sleep(1); \
;     if ((++_sp & 255u) == 0u) { if (xb_ld(&(bar)[XB_TMO])) break; if (_sp > XB_SPIN_CAP) { atomicAdd(&(bar)[XB_TMO], 1u); break; } } } } while (0)
; __device__ __forceinline__ void xcd_barrier(const XcdBarrier& b) {
;     ...
;             else XB_SPIN(xb_ld(&bar[XB_TOPGEN]) == tg, bar);
;             __builtin_amdgcn_fence(__ATOMIC_ACQUIRE, "agent");
;             xb_add(&bar[XB_XGEN(b.x)], 1u);
;             asm volatile("s_waitcnt vmcnt(0)" ::: "memory");
;         } else {
;             XB_SPIN(xb_ld(&bar[XB_XGEN(b.x)]) == gen, bar);
;             __builtin_amdgcn_fence(__ATOMIC_ACQUIRE, "agent");
;             asm volatile("s_waitcnt vmcnt(0)" ::: "memory");
;         }
.Lxb_local_n:
	s_mov_b32 s3, 0
	global_load_dword v2, v173, s[8:9] sc1
	s_sleep 12
.Lxb_gen_n:
	global_load_dword v3, v173, s[8:9] sc1
	s_waitcnt vmcnt(1)
	v_readfirstlane_b32 s5, v2
	s_nop 3
	s_cmp_ge_u32 s5, s32
	s_cbranch_scc1 .Lxb_gen_n_done
	global_load_dword v2, v173, s[8:9] sc1
	s_waitcnt vmcnt(1)
	v_readfirstlane_b32 s5, v3
	s_nop 3
	s_cmp_ge_u32 s5, s32
	s_cbranch_scc1 .Lxb_gen_n_done
	s_add_i32 s3, s3, 1
	s_cmp_lt_u32 s3, 0x40000
	s_cbranch_scc1 .Lxb_gen_n
